# MLA attention epilogue: lane pairs exchange packed halves with v_permlane32_swap, 8 dwordx4 stores per lane instead of 16 dwordx2
# speedup vs baseline: 1.0027x; 1.0027x over previous
; __device__ __forceinline__ unsigned cvt_pk_bf16(float lo, float hi) { unsigned r; asm volatile("v_cvt_pk_bf16_f32 %0, %1, %2" : "=v"(r) : "v"(lo), "v"(hi)); return r; }
; __device__ __forceinline__ void mla_attn_phase(LAS unsigned char* lds, const bf16_t* Q, const bf16_t* KN, const bf16_t* KR, const bf16_t* VT, bf16_t* O, int G, int bx, const int tid) {
;     ...
;         lrun += __shfl_xor(lrun, 32);
;         const float inv = 1.0f / lrun;
;         bf16_t* op = O + (rowbase + q0 + r32) * 2048 + h * 128 + 4 * hi;
; #pragma unroll
;         for (int dvb = 0; dvb < 4; ++dvb)
; #pragma unroll
;             for (int g4 = 0; g4 < 4; ++g4) { u32x2 w; w.x = cvt_pk_bf16(o[dvb][4 * g4] * inv, o[dvb][4 * g4 + 1] * inv); w.y = cvt_pk_bf16(o[dvb][4 * g4 + 2] * inv, o[dvb][4 * g4 + 3] * inv);
;                 *(u32x2*)(op + 32 * dvb + 8 * g4) = w; }
.LBB0_259:
	v_and_b32_e32 v65, 64, v220
	v_xor_b32_e32 v64, 32, v220
	v_add_u32_e32 v65, 64, v65
	v_cmp_lt_i32_e32 vcc, v64, v65
	s_lshl_b32 s30, s38, 7
	s_lshl_b32 s74, s30, 1
	v_cndmask_b32_e32 v64, v220, v64, vcc
	v_lshlrev_b32_e32 v64, 2, v64
	ds_bpermute_b32 v64, v64, v201
	s_add_i32 s46, s46, 1
	s_waitcnt lgkmcnt(0)
	v_add_f32_e32 v66, v201, v64
	v_div_scale_f32 v67, s[38:39], v66, v66, 1.0
	v_rcp_f32_e32 v68, v67
	v_div_scale_f32 v69, vcc, 1.0, v66, 1.0
	v_lshlrev_b64 v[64:65], 12, v[202:203]
	v_fma_f32 v70, -v67, v68, 1.0
	v_fmac_f32_e32 v68, v70, v68
	v_mul_f32_e32 v70, v69, v68
	v_fma_f32 v71, -v67, v70, v69
	v_fmac_f32_e32 v70, v71, v68
	v_fma_f32 v67, -v67, v70, v69
	v_div_fmas_f32 v67, v67, v68, v70
	v_div_fixup_f32 v68, v67, v66, 1.0
	v_lshl_add_u64 v[64:65], s[48:49], 0, v[64:65]
	v_lshl_add_u64 v[64:65], v[64:65], 0, s[74:75]
	v_lshlrev_b32_e32 v66, 2, v184
	v_mov_b32_e32 v67, v181
	v_lshl_add_u64 v[64:65], v[64:65], 0, v[66:67]
	v_mul_f32_e32 v48, v48, v68
	v_mul_f32_e32 v49, v49, v68
	v_mul_f32_e32 v50, v50, v68
	v_mul_f32_e32 v51, v51, v68
	v_mul_f32_e32 v52, v52, v68
	v_mul_f32_e32 v53, v53, v68
	v_mul_f32_e32 v54, v54, v68
	v_mul_f32_e32 v55, v55, v68
	v_cvt_pk_bf16_f32 v48, v48, v49
	v_cvt_pk_bf16_f32 v49, v50, v51
	v_cvt_pk_bf16_f32 v50, v52, v53
	v_cvt_pk_bf16_f32 v51, v54, v55
	v_mul_f32_e32 v56, v56, v68
	v_mul_f32_e32 v57, v57, v68
	v_mul_f32_e32 v58, v58, v68
	v_mul_f32_e32 v59, v59, v68
	v_mul_f32_e32 v60, v60, v68
	v_mul_f32_e32 v61, v61, v68
	v_mul_f32_e32 v62, v62, v68
	v_mul_f32_e32 v63, v63, v68
	v_cvt_pk_bf16_f32 v56, v56, v57
	v_cvt_pk_bf16_f32 v57, v58, v59
	v_cvt_pk_bf16_f32 v58, v60, v61
	v_cvt_pk_bf16_f32 v59, v62, v63
	v_permlane32_swap_b32_e32 v48, v50
	v_permlane32_swap_b32_e32 v49, v51
	global_store_dwordx4 v[64:65], v[48:51], off
	v_mul_f32_e32 v32, v32, v68
	v_mul_f32_e32 v33, v33, v68
	v_mul_f32_e32 v34, v34, v68
	v_mul_f32_e32 v35, v35, v68
	v_mul_f32_e32 v36, v36, v68
	v_mul_f32_e32 v37, v37, v68
	v_mul_f32_e32 v38, v38, v68
	v_mul_f32_e32 v39, v39, v68
	v_cvt_pk_bf16_f32 v32, v32, v33
	v_cvt_pk_bf16_f32 v33, v34, v35
	v_cvt_pk_bf16_f32 v34, v36, v37
	v_cvt_pk_bf16_f32 v35, v38, v39
	v_permlane32_swap_b32_e32 v56, v58
	v_permlane32_swap_b32_e32 v57, v59
	global_store_dwordx4 v[64:65], v[56:59], off offset:32
	v_mul_f32_e32 v40, v40, v68
	v_mul_f32_e32 v41, v41, v68
	v_mul_f32_e32 v42, v42, v68
	v_mul_f32_e32 v43, v43, v68
	v_mul_f32_e32 v44, v44, v68
	v_mul_f32_e32 v45, v45, v68
	v_mul_f32_e32 v46, v46, v68
	v_mul_f32_e32 v47, v47, v68
	v_cvt_pk_bf16_f32 v40, v40, v41
	v_cvt_pk_bf16_f32 v41, v42, v43
	v_cvt_pk_bf16_f32 v42, v44, v45
	v_cvt_pk_bf16_f32 v43, v46, v47
	v_permlane32_swap_b32_e32 v32, v34
	v_permlane32_swap_b32_e32 v33, v35
	global_store_dwordx4 v[64:65], v[32:35], off offset:64
	v_mul_f32_e32 v16, v16, v68
	v_mul_f32_e32 v17, v17, v68
	v_mul_f32_e32 v18, v18, v68
	v_mul_f32_e32 v19, v19, v68
	v_mul_f32_e32 v20, v20, v68
	v_mul_f32_e32 v21, v21, v68
	v_mul_f32_e32 v22, v22, v68
	v_mul_f32_e32 v23, v23, v68
	v_cvt_pk_bf16_f32 v16, v16, v17
	v_cvt_pk_bf16_f32 v17, v18, v19
	v_cvt_pk_bf16_f32 v18, v20, v21
	v_cvt_pk_bf16_f32 v19, v22, v23
	v_permlane32_swap_b32_e32 v40, v42
	v_permlane32_swap_b32_e32 v41, v43
	global_store_dwordx4 v[64:65], v[40:43], off offset:96
	v_mul_f32_e32 v24, v24, v68
	v_mul_f32_e32 v25, v25, v68
	v_mul_f32_e32 v26, v26, v68
	v_mul_f32_e32 v27, v27, v68
	v_mul_f32_e32 v28, v28, v68
	v_mul_f32_e32 v29, v29, v68
	v_mul_f32_e32 v30, v30, v68
	v_mul_f32_e32 v31, v31, v68
	v_cvt_pk_bf16_f32 v24, v24, v25
	v_cvt_pk_bf16_f32 v25, v26, v27
	v_cvt_pk_bf16_f32 v26, v28, v29
	v_cvt_pk_bf16_f32 v27, v30, v31
	v_permlane32_swap_b32_e32 v16, v18
	v_permlane32_swap_b32_e32 v17, v19
	global_store_dwordx4 v[64:65], v[16:19], off offset:128
	v_mul_f32_e32 v0, v0, v68
	v_mul_f32_e32 v1, v1, v68
	v_mul_f32_e32 v2, v2, v68
	v_mul_f32_e32 v3, v3, v68
	v_mul_f32_e32 v4, v4, v68
	v_mul_f32_e32 v5, v5, v68
	v_mul_f32_e32 v6, v6, v68
	v_mul_f32_e32 v7, v7, v68
	v_cvt_pk_bf16_f32 v0, v0, v1
	v_cvt_pk_bf16_f32 v1, v2, v3
	v_cvt_pk_bf16_f32 v2, v4, v5
	v_cvt_pk_bf16_f32 v3, v6, v7
	v_permlane32_swap_b32_e32 v24, v26
	v_permlane32_swap_b32_e32 v25, v27
	global_store_dwordx4 v[64:65], v[24:27], off offset:160
	v_mul_f32_e32 v8, v8, v68
	v_mul_f32_e32 v9, v9, v68
	v_mul_f32_e32 v10, v10, v68
	v_mul_f32_e32 v11, v11, v68
	v_mul_f32_e32 v12, v12, v68
	v_mul_f32_e32 v13, v13, v68
	v_mul_f32_e32 v14, v14, v68
	v_mul_f32_e32 v15, v15, v68
	v_cvt_pk_bf16_f32 v8, v8, v9
	v_cvt_pk_bf16_f32 v9, v10, v11
	v_cvt_pk_bf16_f32 v10, v12, v13
	v_cvt_pk_bf16_f32 v11, v14, v15
	v_permlane32_swap_b32_e32 v0, v2
	v_permlane32_swap_b32_e32 v1, v3
	global_store_dwordx4 v[64:65], v[0:3], off offset:192
	s_nop 1
	v_permlane32_swap_b32_e32 v8, v10
	v_permlane32_swap_b32_e32 v9, v11
	global_store_dwordx4 v[64:65], v[8:11], off offset:224
	s_mov_b64 s[38:39], 0
	v_readlane_b32 s74, v255, 40
